# att15 = att14 + RG-LRU final-pass conv stage: rows 1..15 loaded right behind row 0 into their own registers, counted waits per row (was vmcnt(1) after each load)
# baseline (speedup 1.0000x reference)
.LBB0_455:
	s_or_b64 exec, exec, s[4:5]
	v_ashrrev_i32_e32 v55, 31, v54
	v_lshl_add_u64 v[58:59], s[2:3], 0, v[54:55]
	v_lshlrev_b64 v[58:59], 11, v[58:59]
	v_lshl_add_u64 v[58:59], v[52:53], 0, v[58:59]
	global_load_dwordx4 v[84:87], v[58:59], off
	s_mov_b64 s[98:99], 0x1000
	global_load_dwordx4 v[88:91], v[58:59], off offset:2048
	v_lshl_add_u64 v[252:253], v[58:59], 0, s[98:99]
	global_load_dwordx4 v[192:195], v[252:253], off
	global_load_dwordx4 v[196:199], v[252:253], off offset:2048
	v_lshl_add_u64 v[252:253], v[252:253], 0, s[98:99]
	global_load_dwordx4 v[200:203], v[252:253], off
	global_load_dwordx4 v[204:207], v[252:253], off offset:2048
	v_lshl_add_u64 v[252:253], v[252:253], 0, s[98:99]
	global_load_dwordx4 v[208:211], v[252:253], off
	global_load_dwordx4 v[212:215], v[252:253], off offset:2048
	v_lshl_add_u64 v[252:253], v[252:253], 0, s[98:99]
	global_load_dwordx4 v[216:219], v[252:253], off
	global_load_dwordx4 v[220:223], v[252:253], off offset:2048
	v_lshl_add_u64 v[252:253], v[252:253], 0, s[98:99]
	global_load_dwordx4 v[224:227], v[252:253], off
	global_load_dwordx4 v[228:231], v[252:253], off offset:2048
	v_lshl_add_u64 v[252:253], v[252:253], 0, s[98:99]
	global_load_dwordx4 v[232:235], v[252:253], off
	global_load_dwordx4 v[236:239], v[252:253], off offset:2048
	v_lshl_add_u64 v[252:253], v[252:253], 0, s[98:99]
	global_load_dwordx4 v[240:243], v[252:253], off
	global_load_dwordx4 v[248:251], v[252:253], off offset:2048
	s_waitcnt vmcnt(16)
	v_lshlrev_b32_e32 v66, 16, v46
	v_and_b32_e32 v76, 0xffff0000, v46
	v_mov_b32_e32 v46, v32
	v_mov_b32_e32 v32, v0
	v_or_b32_e32 v0, 1, v54
	v_lshlrev_b32_e32 v67, 16, v47
	v_and_b32_e32 v77, 0xffff0000, v47
	v_mov_b32_e32 v47, v34
	v_mov_b32_e32 v34, v33
	v_mov_b32_e32 v33, v2
	v_mov_b32_e32 v2, v1
	v_ashrrev_i32_e32 v1, 31, v0
	v_lshl_add_u64 v[0:1], s[2:3], 0, v[0:1]
	v_lshlrev_b64 v[0:1], 11, v[0:1]
	v_lshl_add_u64 v[0:1], v[52:53], 0, v[0:1]
	v_lshlrev_b32_e32 v60, 16, v40
	v_and_b32_e32 v58, 0xffff0000, v40
	v_mov_b32_e32 v40, v20
	v_mov_b32_e32 v20, v8
	v_or_b32_e32 v8, 2, v54
	v_lshlrev_b32_e32 v61, 16, v41
	v_and_b32_e32 v59, 0xffff0000, v41
	v_mov_b32_e32 v41, v22
	v_mov_b32_e32 v22, v21
	v_mov_b32_e32 v21, v10
	v_mov_b32_e32 v10, v9
	v_ashrrev_i32_e32 v9, 31, v8
	v_lshlrev_b32_e32 v71, 16, v51
	v_lshlrev_b32_e32 v70, 16, v50
	v_and_b32_e32 v69, 0xffff0000, v51
	v_and_b32_e32 v68, 0xffff0000, v50
	v_lshlrev_b32_e32 v62, 16, v44
	v_lshlrev_b32_e32 v63, 16, v45
	v_mov_b32_e32 v50, v36
	v_mov_b32_e32 v51, v38
	v_lshl_add_u64 v[8:9], s[2:3], 0, v[8:9]
	v_lshlrev_b32_e32 v75, 16, v49
	v_lshlrev_b32_e32 v74, 16, v48
	v_and_b32_e32 v73, 0xffff0000, v49
	v_and_b32_e32 v72, 0xffff0000, v48
	v_mov_b32_e32 v48, v16
	v_mov_b32_e32 v49, v18
	v_mov_b32_e32 v18, v17
	v_mov_b32_e32 v16, v12
	v_mov_b32_e32 v17, v14
	v_mov_b32_e32 v14, v13
	v_mov_b32_e32 v12, v24
	v_mov_b32_e32 v13, v26
	v_mov_b32_e32 v26, v25
	v_pk_fma_f32 v[24:25], v[46:47], v[62:63], v[50:51]
	v_lshlrev_b64 v[8:9], 11, v[8:9]
	v_and_b32_e32 v64, 0xffff0000, v44
	v_and_b32_e32 v65, 0xffff0000, v45
	v_mov_b32_e32 v38, v37
	v_pk_fma_f32 v[24:25], v[48:49], v[74:75], v[24:25]
	v_lshl_add_u64 v[8:9], v[52:53], 0, v[8:9]
	v_lshl_add_u32 v44, v56, 1, 0
	v_mov_b32_e32 v56, v28
	v_mov_b32_e32 v57, v30
	v_mov_b32_e32 v30, v29
	v_lshlrev_b32_e32 v81, 16, v43
	v_lshlrev_b32_e32 v80, 16, v42
	v_and_b32_e32 v79, 0xffff0000, v43
	v_and_b32_e32 v78, 0xffff0000, v42
	v_pk_fma_f32 v[28:29], v[34:35], v[64:65], v[38:39]
	v_pk_fma_f32 v[36:37], v[16:17], v[66:67], v[12:13]
	v_pk_fma_f32 v[42:43], v[40:41], v[60:61], v[24:25]
	v_pk_fma_f32 v[28:29], v[18:19], v[72:73], v[28:29]
	v_pk_fma_f32 v[76:77], v[14:15], v[76:77], v[26:27]
	v_pk_fma_f32 v[28:29], v[22:23], v[58:59], v[28:29]
	v_pk_fma_f32 v[76:77], v[2:3], v[68:69], v[76:77]
	v_pk_fma_f32 v[36:37], v[32:33], v[70:71], v[36:37]
	v_pk_fma_f32 v[68:69], v[14:15], v[68:69], v[26:27]
	v_pk_fma_f32 v[70:71], v[16:17], v[70:71], v[12:13]
	v_pk_fma_f32 v[68:69], v[2:3], v[78:79], v[68:69]
	v_pk_fma_f32 v[70:71], v[32:33], v[80:81], v[70:71]
	v_or_b32_e32 v82, 15, v82
	s_ashr_i32 s47, s45, 6
	s_waitcnt vmcnt(15)
	v_lshlrev_b32_e32 v67, 16, v85
	v_lshlrev_b32_e32 v66, 16, v84
	v_and_b32_e32 v65, 0xffff0000, v85
	v_and_b32_e32 v64, 0xffff0000, v84
	v_lshlrev_b32_e32 v63, 16, v87
	v_lshlrev_b32_e32 v62, 16, v86
	v_and_b32_e32 v25, 0xffff0000, v87
	v_and_b32_e32 v24, 0xffff0000, v86
	v_mov_b32_e32 v1, v6
	v_pk_fma_f32 v[28:29], v[30:31], v[64:65], v[28:29]
	v_mov_b32_e32 v6, v5
	v_mov_b32_e32 v0, v4
	v_pk_fma_f32 v[42:43], v[56:57], v[66:67], v[42:43]
	v_pk_fma_f32 v[4:5], v[6:7], v[78:79], v[76:77]
	v_bfe_u32 v76, v29, 16, 1
	v_bfe_u32 v8, v28, 16, 1
	v_add3_u32 v8, v28, v8, s27
	v_add3_u32 v9, v29, v76, s27
	v_bfe_u32 v28, v42, 16, 1
	v_bfe_u32 v29, v43, 16, 1
	v_pk_fma_f32 v[36:37], v[0:1], v[80:81], v[36:37]
	v_pk_fma_f32 v[4:5], v[10:11], v[24:25], v[4:5]
	v_add3_u32 v29, v43, v29, s27
	v_add3_u32 v28, v42, v28, s27
	v_pk_fma_f32 v[36:37], v[20:21], v[62:63], v[36:37]
	v_bfe_u32 v45, v5, 16, 1
	v_bfe_u32 v55, v4, 16, 1
	v_lshrrev_b32_e32 v28, 16, v28
	v_lshrrev_b32_e32 v29, 16, v29
	v_add3_u32 v4, v4, v55, s27
	v_add3_u32 v5, v5, v45, s27
	v_bfe_u32 v45, v36, 16, 1
	v_bfe_u32 v55, v37, 16, 1
	v_and_or_b32 v93, v9, s26, v29
	v_and_or_b32 v92, v8, s26, v28
	v_pk_fma_f32 v[28:29], v[46:47], v[74:75], v[50:51]
	v_add3_u32 v37, v37, v55, s27
	v_add3_u32 v36, v36, v45, s27
	v_pk_fma_f32 v[28:29], v[48:49], v[60:61], v[28:29]
	v_lshrrev_b32_e32 v36, 16, v36
	v_lshrrev_b32_e32 v37, 16, v37
	s_waitcnt vmcnt(14)
	v_lshlrev_b32_e32 v77, 16, v89
	v_lshlrev_b32_e32 v76, 16, v88
	v_pk_fma_f32 v[28:29], v[40:41], v[66:67], v[28:29]
	v_and_or_b32 v95, v5, s26, v37
	v_and_or_b32 v94, v4, s26, v36
	v_pk_fma_f32 v[36:37], v[56:57], v[76:77], v[28:29]
	v_pk_fma_f32 v[28:29], v[34:35], v[72:73], v[38:39]
	v_or_b32_e32 v72, 3, v54
	v_pk_fma_f32 v[28:29], v[18:19], v[58:59], v[28:29]
	v_ashrrev_i32_e32 v73, 31, v72
	v_and_b32_e32 v9, 0xffff0000, v89
	v_and_b32_e32 v8, 0xffff0000, v88
	v_pk_fma_f32 v[28:29], v[22:23], v[64:65], v[28:29]
	v_lshl_add_u64 v[72:73], s[2:3], 0, v[72:73]
	v_pk_fma_f32 v[42:43], v[30:31], v[8:9], v[28:29]
	v_and_b32_e32 v29, 0xffff0000, v91
	v_and_b32_e32 v28, 0xffff0000, v90
	v_pk_fma_f32 v[68:69], v[6:7], v[24:25], v[68:69]
	v_lshlrev_b64 v[72:73], 11, v[72:73]
	v_lshlrev_b32_e32 v75, 16, v91
	v_lshlrev_b32_e32 v74, 16, v90
	v_pk_fma_f32 v[70:71], v[0:1], v[62:63], v[70:71]
	v_pk_fma_f32 v[68:69], v[10:11], v[28:29], v[68:69]
	v_lshl_add_u64 v[72:73], v[52:53], 0, v[72:73]
	v_mad_u64_u32 v[4:5], s[0:1], v54, s30, v[44:45]
	v_pk_fma_f32 v[70:71], v[20:21], v[74:75], v[70:71]
	v_bfe_u32 v45, v68, 16, 1
	v_bfe_u32 v55, v43, 16, 1
	v_bfe_u32 v72, v42, 16, 1
	v_bfe_u32 v5, v69, 16, 1
	v_add3_u32 v42, v42, v72, s27
	v_add3_u32 v43, v43, v55, s27
	v_add3_u32 v45, v68, v45, s27
	v_bfe_u32 v55, v36, 16, 1
	v_bfe_u32 v68, v37, 16, 1
	v_bfe_u32 v72, v71, 16, 1
	v_add3_u32 v5, v69, v5, s27
	v_bfe_u32 v69, v70, 16, 1
	v_add3_u32 v71, v71, v72, s27
	v_add3_u32 v37, v37, v68, s27
	v_add3_u32 v36, v36, v55, s27
	v_add3_u32 v69, v70, v69, s27
	v_lshrrev_b32_e32 v36, 16, v36
	v_lshrrev_b32_e32 v37, 16, v37
	v_lshrrev_b32_e32 v68, 16, v71
	v_lshrrev_b32_e32 v55, 16, v69
	v_and_or_b32 v71, v5, s26, v68
	v_and_or_b32 v69, v43, s26, v37
	v_and_or_b32 v68, v42, s26, v36
	v_pk_fma_f32 v[42:43], v[46:47], v[60:61], v[50:51]
	s_waitcnt vmcnt(13)
	v_lshlrev_b32_e32 v73, 16, v193
	v_pk_fma_f32 v[42:43], v[48:49], v[66:67], v[42:43]
	v_lshlrev_b32_e32 v72, 16, v192
	v_pk_fma_f32 v[42:43], v[40:41], v[76:77], v[42:43]
	v_pk_fma_f32 v[78:79], v[14:15], v[78:79], v[26:27]
	v_pk_fma_f32 v[60:61], v[56:57], v[72:73], v[42:43]
	v_pk_fma_f32 v[42:43], v[34:35], v[58:59], v[38:39]
	v_and_b32_e32 v37, 0xffff0000, v193
	v_pk_fma_f32 v[42:43], v[18:19], v[64:65], v[42:43]
	v_and_b32_e32 v36, 0xffff0000, v192
	v_pk_fma_f32 v[42:43], v[22:23], v[8:9], v[42:43]
	v_pk_fma_f32 v[78:79], v[2:3], v[24:25], v[78:79]
	v_pk_fma_f32 v[58:59], v[30:31], v[36:37], v[42:43]
	v_and_b32_e32 v43, 0xffff0000, v195
	v_and_b32_e32 v42, 0xffff0000, v194
	v_pk_fma_f32 v[78:79], v[6:7], v[28:29], v[78:79]
	v_and_or_b32 v70, v45, s26, v55
	v_pk_fma_f32 v[84:85], v[10:11], v[42:43], v[78:79]
	v_or_b32_e32 v78, 4, v54
	v_ashrrev_i32_e32 v79, 31, v78
	v_lshl_add_u64 v[78:79], s[2:3], 0, v[78:79]
	ds_write_b128 v4, v[68:71] offset:528
	v_pk_fma_f32 v[68:69], v[16:17], v[80:81], v[12:13]
	v_lshlrev_b64 v[78:79], 11, v[78:79]
	v_pk_fma_f32 v[68:69], v[32:33], v[62:63], v[68:69]
	v_lshl_add_u64 v[78:79], v[52:53], 0, v[78:79]
	v_lshlrev_b32_e32 v71, 16, v195
	v_lshlrev_b32_e32 v70, 16, v194
	v_pk_fma_f32 v[68:69], v[0:1], v[74:75], v[68:69]
	v_pk_fma_f32 v[68:69], v[20:21], v[70:71], v[68:69]
	v_bfe_u32 v45, v84, 16, 1
	v_bfe_u32 v5, v85, 16, 1
	v_add3_u32 v45, v84, v45, s27
	v_bfe_u32 v84, v68, 16, 1
	v_add3_u32 v5, v85, v5, s27
	v_bfe_u32 v85, v69, 16, 1
	v_add3_u32 v68, v68, v84, s27
	v_or_b32_e32 v84, 5, v54
	v_add3_u32 v69, v69, v85, s27
	v_ashrrev_i32_e32 v85, 31, v84
	v_lshl_add_u64 v[84:85], s[2:3], 0, v[84:85]
	v_lshlrev_b64 v[84:85], 11, v[84:85]
	v_lshl_add_u64 v[84:85], v[52:53], 0, v[84:85]
	v_bfe_u32 v55, v59, 16, 1
	v_bfe_u32 v83, v58, 16, 1
	v_add3_u32 v58, v58, v83, s27
	v_add3_u32 v55, v59, v55, s27
	v_bfe_u32 v59, v60, 16, 1
	v_bfe_u32 v83, v61, 16, 1
	v_add3_u32 v61, v61, v83, s27
	v_add3_u32 v59, v60, v59, s27
	v_lshrrev_b32_e32 v83, 16, v59
	v_lshrrev_b32_e32 v59, 16, v61
	v_lshrrev_b32_e32 v60, 16, v68
	v_lshrrev_b32_e32 v61, 16, v69
	v_and_or_b32 v61, v5, s26, v61
	v_and_or_b32 v60, v45, s26, v60
	v_and_or_b32 v59, v55, s26, v59
	v_and_or_b32 v58, v58, s26, v83
	ds_write_b128 v4, v[58:61] offset:1056
	v_pk_fma_f32 v[60:61], v[46:47], v[66:67], v[50:51]
	s_waitcnt vmcnt(12)
	v_lshlrev_b32_e32 v69, 16, v197
	v_pk_fma_f32 v[60:61], v[48:49], v[76:77], v[60:61]
	v_lshlrev_b32_e32 v68, 16, v196
	v_pk_fma_f32 v[60:61], v[40:41], v[72:73], v[60:61]
	v_and_b32_e32 v59, 0xffff0000, v197
	v_and_b32_e32 v58, 0xffff0000, v196
	v_pk_fma_f32 v[88:89], v[56:57], v[68:69], v[60:61]
	v_pk_fma_f32 v[60:61], v[34:35], v[64:65], v[38:39]
	v_pk_fma_f32 v[24:25], v[14:15], v[24:25], v[26:27]
	v_pk_fma_f32 v[60:61], v[18:19], v[8:9], v[60:61]
	v_pk_fma_f32 v[62:63], v[16:17], v[62:63], v[12:13]
	v_pk_fma_f32 v[60:61], v[22:23], v[36:37], v[60:61]
	v_pk_fma_f32 v[24:25], v[2:3], v[28:29], v[24:25]
	v_pk_fma_f32 v[64:65], v[30:31], v[58:59], v[60:61]
	v_and_b32_e32 v61, 0xffff0000, v199
	v_and_b32_e32 v60, 0xffff0000, v198
	v_pk_fma_f32 v[62:63], v[32:33], v[74:75], v[62:63]
	v_pk_fma_f32 v[24:25], v[6:7], v[42:43], v[24:25]
	v_lshlrev_b32_e32 v67, 16, v199
	v_lshlrev_b32_e32 v66, 16, v198
	v_pk_fma_f32 v[62:63], v[0:1], v[70:71], v[62:63]
	v_pk_fma_f32 v[24:25], v[10:11], v[60:61], v[24:25]
	v_pk_fma_f32 v[62:63], v[20:21], v[66:67], v[62:63]
	v_bfe_u32 v5, v25, 16, 1
	v_bfe_u32 v45, v24, 16, 1
	v_bfe_u32 v55, v65, 16, 1
	v_bfe_u32 v83, v64, 16, 1
	v_add3_u32 v83, v64, v83, s27
	v_add3_u32 v55, v65, v55, s27
	v_add3_u32 v24, v24, v45, s27
	v_add3_u32 v5, v25, v5, s27
	v_bfe_u32 v25, v88, 16, 1
	v_bfe_u32 v45, v89, 16, 1
	v_bfe_u32 v64, v62, 16, 1
	v_bfe_u32 v65, v63, 16, 1
	v_add3_u32 v63, v63, v65, s27
	v_add3_u32 v62, v62, v64, s27
	v_add3_u32 v45, v89, v45, s27
	v_add3_u32 v25, v88, v25, s27
	v_lshrrev_b32_e32 v25, 16, v25
	v_lshrrev_b32_e32 v45, 16, v45
	v_lshrrev_b32_e32 v62, 16, v62
	v_lshrrev_b32_e32 v63, 16, v63
	v_and_or_b32 v65, v5, s26, v63
	v_and_or_b32 v64, v24, s26, v62
	v_and_or_b32 v63, v55, s26, v45
	v_and_or_b32 v62, v83, s26, v25
	ds_write_b128 v4, v[62:65] offset:1584
	v_pk_fma_f32 v[62:63], v[46:47], v[76:77], v[50:51]
	v_or_b32_e32 v76, 6, v54
	v_ashrrev_i32_e32 v77, 31, v76
	v_lshl_add_u64 v[76:77], s[2:3], 0, v[76:77]
	v_lshlrev_b64 v[76:77], 11, v[76:77]
	v_lshl_add_u64 v[76:77], v[52:53], 0, v[76:77]
	s_waitcnt vmcnt(11)
	v_lshlrev_b32_e32 v65, 16, v201
	v_lshlrev_b32_e32 v64, 16, v200
	v_and_b32_e32 v25, 0xffff0000, v201
	v_and_b32_e32 v24, 0xffff0000, v200
	v_pk_fma_f32 v[8:9], v[34:35], v[8:9], v[38:39]
	v_pk_fma_f32 v[62:63], v[48:49], v[72:73], v[62:63]
	v_pk_fma_f32 v[8:9], v[18:19], v[36:37], v[8:9]
	v_pk_fma_f32 v[74:75], v[16:17], v[74:75], v[12:13]
	v_pk_fma_f32 v[28:29], v[14:15], v[28:29], v[26:27]
	v_pk_fma_f32 v[62:63], v[40:41], v[68:69], v[62:63]
	v_pk_fma_f32 v[8:9], v[22:23], v[58:59], v[8:9]
	v_pk_fma_f32 v[74:75], v[32:33], v[70:71], v[74:75]
	v_pk_fma_f32 v[28:29], v[2:3], v[42:43], v[28:29]
	v_pk_fma_f32 v[88:89], v[56:57], v[64:65], v[62:63]
	v_pk_fma_f32 v[90:91], v[30:31], v[24:25], v[8:9]
	v_lshlrev_b32_e32 v63, 16, v203
	v_lshlrev_b32_e32 v62, 16, v202
	v_and_b32_e32 v9, 0xffff0000, v203
	v_and_b32_e32 v8, 0xffff0000, v202
	v_pk_fma_f32 v[74:75], v[0:1], v[66:67], v[74:75]
	v_pk_fma_f32 v[28:29], v[6:7], v[60:61], v[28:29]
	v_pk_fma_f32 v[74:75], v[20:21], v[62:63], v[74:75]
	v_pk_fma_f32 v[28:29], v[10:11], v[8:9], v[28:29]
	v_bfe_u32 v81, v74, 16, 1
	v_bfe_u32 v5, v29, 16, 1
	v_bfe_u32 v45, v28, 16, 1
	v_add3_u32 v5, v29, v5, s27
	v_bfe_u32 v29, v88, 16, 1
	v_bfe_u32 v83, v75, 16, 1
	v_add3_u32 v74, v74, v81, s27
	v_bfe_u32 v80, v90, 16, 1
	v_add3_u32 v28, v28, v45, s27
	v_add3_u32 v75, v75, v83, s27
	v_add3_u32 v29, v88, v29, s27
	v_lshrrev_b32_e32 v74, 16, v74
	v_bfe_u32 v55, v91, 16, 1
	v_add3_u32 v80, v90, v80, s27
	v_lshrrev_b32_e32 v29, 16, v29
	v_lshrrev_b32_e32 v75, 16, v75
	v_and_or_b32 v90, v28, s26, v74
	s_waitcnt vmcnt(10)
	v_lshlrev_b32_e32 v74, 16, v204
	v_and_b32_e32 v28, 0xffff0000, v204
	v_or_b32_e32 v84, 7, v54
	v_add3_u32 v55, v91, v55, s27
	v_bfe_u32 v45, v89, 16, 1
	v_and_or_b32 v91, v5, s26, v75
	v_and_or_b32 v88, v80, s26, v29
	v_lshlrev_b32_e32 v75, 16, v205
	v_and_b32_e32 v29, 0xffff0000, v205
	v_ashrrev_i32_e32 v85, 31, v84
	v_add3_u32 v45, v89, v45, s27
	v_pk_fma_f32 v[72:73], v[46:47], v[72:73], v[50:51]
	v_pk_fma_f32 v[36:37], v[34:35], v[36:37], v[38:39]
	v_lshl_add_u64 v[84:85], s[2:3], 0, v[84:85]
	v_lshrrev_b32_e32 v45, 16, v45
	v_pk_fma_f32 v[72:73], v[48:49], v[68:69], v[72:73]
	v_pk_fma_f32 v[36:37], v[18:19], v[58:59], v[36:37]
	v_lshlrev_b64 v[84:85], 11, v[84:85]
	v_and_or_b32 v89, v55, s26, v45
	v_pk_fma_f32 v[72:73], v[40:41], v[64:65], v[72:73]
	v_pk_fma_f32 v[36:37], v[22:23], v[24:25], v[36:37]
	v_lshl_add_u64 v[84:85], v[52:53], 0, v[84:85]
	ds_write_b128 v4, v[88:91] offset:2112
	v_pk_fma_f32 v[80:81], v[56:57], v[74:75], v[72:73]
	v_pk_fma_f32 v[88:89], v[30:31], v[28:29], v[36:37]
	v_lshlrev_b32_e32 v73, 16, v207
	v_lshlrev_b32_e32 v72, 16, v206
	v_and_b32_e32 v37, 0xffff0000, v207
	v_and_b32_e32 v36, 0xffff0000, v206
	v_pk_fma_f32 v[42:43], v[14:15], v[42:43], v[26:27]
	v_pk_fma_f32 v[70:71], v[16:17], v[70:71], v[12:13]
	v_pk_fma_f32 v[42:43], v[2:3], v[60:61], v[42:43]
	v_pk_fma_f32 v[70:71], v[32:33], v[66:67], v[70:71]
	v_pk_fma_f32 v[42:43], v[6:7], v[8:9], v[42:43]
	v_pk_fma_f32 v[70:71], v[0:1], v[62:63], v[70:71]
	v_pk_fma_f32 v[42:43], v[10:11], v[36:37], v[42:43]
	v_pk_fma_f32 v[70:71], v[20:21], v[72:73], v[70:71]
	v_bfe_u32 v5, v43, 16, 1
	v_bfe_u32 v45, v42, 16, 1
	v_bfe_u32 v55, v89, 16, 1
	v_bfe_u32 v83, v88, 16, 1
	v_add3_u32 v83, v88, v83, s27
	v_add3_u32 v55, v89, v55, s27
	v_add3_u32 v42, v42, v45, s27
	v_add3_u32 v5, v43, v5, s27
	v_bfe_u32 v43, v80, 16, 1
	v_bfe_u32 v45, v81, 16, 1
	v_bfe_u32 v88, v70, 16, 1
	v_bfe_u32 v89, v71, 16, 1
	v_add3_u32 v71, v71, v89, s27
	v_add3_u32 v70, v70, v88, s27
	v_add3_u32 v45, v81, v45, s27
	v_add3_u32 v43, v80, v43, s27
	v_pk_fma_f32 v[68:69], v[46:47], v[68:69], v[50:51]
	v_pk_fma_f32 v[58:59], v[34:35], v[58:59], v[38:39]
	v_lshrrev_b32_e32 v43, 16, v43
	v_lshrrev_b32_e32 v45, 16, v45
	v_lshrrev_b32_e32 v70, 16, v70
	v_lshrrev_b32_e32 v71, 16, v71
	v_pk_fma_f32 v[68:69], v[48:49], v[64:65], v[68:69]
	v_pk_fma_f32 v[58:59], v[18:19], v[24:25], v[58:59]
	v_and_or_b32 v91, v5, s26, v71
	v_and_or_b32 v90, v42, s26, v70
	v_and_or_b32 v89, v55, s26, v45
	v_and_or_b32 v88, v83, s26, v43
	s_waitcnt vmcnt(9)
	v_lshlrev_b32_e32 v71, 16, v209
	v_lshlrev_b32_e32 v70, 16, v208
	v_and_b32_e32 v43, 0xffff0000, v209
	v_and_b32_e32 v42, 0xffff0000, v208
	v_pk_fma_f32 v[68:69], v[40:41], v[74:75], v[68:69]
	v_pk_fma_f32 v[58:59], v[22:23], v[28:29], v[58:59]
	ds_write_b128 v4, v[88:91] offset:2640
	v_pk_fma_f32 v[76:77], v[56:57], v[70:71], v[68:69]
	v_pk_fma_f32 v[88:89], v[30:31], v[42:43], v[58:59]
	v_lshlrev_b32_e32 v68, 16, v210
	v_and_b32_e32 v58, 0xffff0000, v210
	v_or_b32_e32 v78, 8, v54
	v_lshlrev_b32_e32 v69, 16, v211
	v_and_b32_e32 v59, 0xffff0000, v211
	v_ashrrev_i32_e32 v79, 31, v78
	v_lshl_add_u64 v[78:79], s[2:3], 0, v[78:79]
	v_lshlrev_b64 v[78:79], 11, v[78:79]
	v_pk_fma_f32 v[60:61], v[14:15], v[60:61], v[26:27]
	v_lshl_add_u64 v[78:79], v[52:53], 0, v[78:79]
	v_pk_fma_f32 v[66:67], v[16:17], v[66:67], v[12:13]
	v_pk_fma_f32 v[60:61], v[2:3], v[8:9], v[60:61]
	v_pk_fma_f32 v[66:67], v[32:33], v[62:63], v[66:67]
	v_pk_fma_f32 v[60:61], v[6:7], v[36:37], v[60:61]
	v_pk_fma_f32 v[66:67], v[0:1], v[72:73], v[66:67]
	v_pk_fma_f32 v[60:61], v[10:11], v[58:59], v[60:61]
	v_pk_fma_f32 v[66:67], v[20:21], v[68:69], v[66:67]
	v_bfe_u32 v45, v60, 16, 1
	v_bfe_u32 v83, v88, 16, 1
	v_bfe_u32 v5, v61, 16, 1
	v_bfe_u32 v55, v89, 16, 1
	v_add3_u32 v83, v88, v83, s27
	v_add3_u32 v45, v60, v45, s27
	v_bfe_u32 v60, v76, 16, 1
	v_bfe_u32 v88, v66, 16, 1
	v_add3_u32 v55, v89, v55, s27
	v_add3_u32 v5, v61, v5, s27
	v_bfe_u32 v61, v77, 16, 1
	v_bfe_u32 v89, v67, 16, 1
	v_add3_u32 v66, v66, v88, s27
	v_add3_u32 v60, v76, v60, s27
	v_add3_u32 v67, v67, v89, s27
	v_add3_u32 v61, v77, v61, s27
	v_lshrrev_b32_e32 v60, 16, v60
	v_lshrrev_b32_e32 v66, 16, v66
	v_lshrrev_b32_e32 v61, 16, v61
	v_lshrrev_b32_e32 v67, 16, v67
	v_and_or_b32 v90, v45, s26, v66
	v_and_or_b32 v88, v83, s26, v60
	s_waitcnt vmcnt(8)
	v_lshlrev_b32_e32 v66, 16, v212
	v_and_b32_e32 v60, 0xffff0000, v212
	v_or_b32_e32 v84, 9, v54
	v_and_or_b32 v91, v5, s26, v67
	v_and_or_b32 v89, v55, s26, v61
	v_lshlrev_b32_e32 v67, 16, v213
	v_and_b32_e32 v61, 0xffff0000, v213
	v_ashrrev_i32_e32 v85, 31, v84
	v_pk_fma_f32 v[64:65], v[46:47], v[64:65], v[50:51]
	v_pk_fma_f32 v[24:25], v[34:35], v[24:25], v[38:39]
	v_lshl_add_u64 v[84:85], s[2:3], 0, v[84:85]
	v_pk_fma_f32 v[64:65], v[48:49], v[74:75], v[64:65]
	v_pk_fma_f32 v[24:25], v[18:19], v[28:29], v[24:25]
	v_lshlrev_b64 v[84:85], 11, v[84:85]
	v_pk_fma_f32 v[64:65], v[40:41], v[70:71], v[64:65]
	v_pk_fma_f32 v[24:25], v[22:23], v[42:43], v[24:25]
	v_lshl_add_u64 v[84:85], v[52:53], 0, v[84:85]
	ds_write_b128 v4, v[88:91] offset:3168
	v_pk_fma_f32 v[76:77], v[56:57], v[66:67], v[64:65]
	v_pk_fma_f32 v[88:89], v[30:31], v[60:61], v[24:25]
	v_lshlrev_b32_e32 v65, 16, v215
	v_lshlrev_b32_e32 v64, 16, v214
	v_and_b32_e32 v25, 0xffff0000, v215
	v_and_b32_e32 v24, 0xffff0000, v214
	v_pk_fma_f32 v[62:63], v[16:17], v[62:63], v[12:13]
	v_pk_fma_f32 v[8:9], v[14:15], v[8:9], v[26:27]
	v_pk_fma_f32 v[62:63], v[32:33], v[72:73], v[62:63]
	v_pk_fma_f32 v[8:9], v[2:3], v[36:37], v[8:9]
	v_pk_fma_f32 v[62:63], v[0:1], v[68:69], v[62:63]
	v_pk_fma_f32 v[8:9], v[6:7], v[58:59], v[8:9]
	v_pk_fma_f32 v[62:63], v[20:21], v[64:65], v[62:63]
	v_bfe_u32 v83, v88, 16, 1
	v_pk_fma_f32 v[8:9], v[10:11], v[24:25], v[8:9]
	v_bfe_u32 v55, v89, 16, 1
	v_add3_u32 v83, v88, v83, s27
	v_bfe_u32 v88, v62, 16, 1
	v_bfe_u32 v5, v9, 16, 1
	v_bfe_u32 v45, v8, 16, 1
	v_add3_u32 v55, v89, v55, s27
	v_bfe_u32 v89, v63, 16, 1
	v_add3_u32 v62, v62, v88, s27
	v_add3_u32 v8, v8, v45, s27
	v_add3_u32 v5, v9, v5, s27
	v_bfe_u32 v9, v76, 16, 1
	v_add3_u32 v63, v63, v89, s27
	v_lshrrev_b32_e32 v62, 16, v62
	v_bfe_u32 v45, v77, 16, 1
	v_add3_u32 v9, v76, v9, s27
	v_lshrrev_b32_e32 v63, 16, v63
	v_and_or_b32 v90, v8, s26, v62
	v_add3_u32 v45, v77, v45, s27
	s_waitcnt vmcnt(7)
	v_lshlrev_b32_e32 v76, 16, v216
	v_and_b32_e32 v62, 0xffff0000, v216
	v_or_b32_e32 v78, 10, v54
	v_and_or_b32 v91, v5, s26, v63
	v_lshlrev_b32_e32 v77, 16, v217
	v_and_b32_e32 v63, 0xffff0000, v217
	v_ashrrev_i32_e32 v79, 31, v78
	v_pk_fma_f32 v[28:29], v[34:35], v[28:29], v[38:39]
	v_lshl_add_u64 v[78:79], s[2:3], 0, v[78:79]
	v_lshrrev_b32_e32 v9, 16, v9
	v_lshrrev_b32_e32 v45, 16, v45
	v_pk_fma_f32 v[28:29], v[18:19], v[42:43], v[28:29]
	v_lshlrev_b64 v[78:79], 11, v[78:79]
	v_and_or_b32 v89, v55, s26, v45
	v_and_or_b32 v88, v83, s26, v9
	v_pk_fma_f32 v[28:29], v[22:23], v[60:61], v[28:29]
	v_lshl_add_u64 v[78:79], v[52:53], 0, v[78:79]
	ds_write_b128 v4, v[88:91] offset:3696
	v_pk_fma_f32 v[8:9], v[46:47], v[74:75], v[50:51]
	v_pk_fma_f32 v[88:89], v[30:31], v[62:63], v[28:29]
	v_lshlrev_b32_e32 v75, 16, v219
	v_lshlrev_b32_e32 v74, 16, v218
	v_and_b32_e32 v29, 0xffff0000, v219
	v_and_b32_e32 v28, 0xffff0000, v218
	v_pk_fma_f32 v[72:73], v[16:17], v[72:73], v[12:13]
	v_pk_fma_f32 v[36:37], v[14:15], v[36:37], v[26:27]
	v_pk_fma_f32 v[72:73], v[32:33], v[68:69], v[72:73]
	v_pk_fma_f32 v[36:37], v[2:3], v[58:59], v[36:37]
	v_pk_fma_f32 v[8:9], v[48:49], v[70:71], v[8:9]
	v_pk_fma_f32 v[72:73], v[0:1], v[64:65], v[72:73]
	v_pk_fma_f32 v[36:37], v[6:7], v[24:25], v[36:37]
	v_pk_fma_f32 v[8:9], v[40:41], v[66:67], v[8:9]
	v_pk_fma_f32 v[72:73], v[20:21], v[74:75], v[72:73]
	v_pk_fma_f32 v[36:37], v[10:11], v[28:29], v[36:37]
	v_bfe_u32 v83, v88, 16, 1
	v_pk_fma_f32 v[8:9], v[56:57], v[76:77], v[8:9]
	v_bfe_u32 v5, v37, 16, 1
	v_add3_u32 v83, v88, v83, s27
	v_bfe_u32 v88, v72, 16, 1
	v_bfe_u32 v45, v36, 16, 1
	v_bfe_u32 v55, v89, 16, 1
	v_add3_u32 v5, v37, v5, s27
	v_bfe_u32 v37, v8, 16, 1
	v_add3_u32 v72, v72, v88, s27
	v_add3_u32 v55, v89, v55, s27
	v_add3_u32 v36, v36, v45, s27
	v_bfe_u32 v89, v73, 16, 1
	v_add3_u32 v8, v8, v37, s27
	v_lshrrev_b32_e32 v37, 16, v72
	v_bfe_u32 v45, v9, 16, 1
	v_add3_u32 v73, v73, v89, s27
	v_and_or_b32 v90, v36, s26, v37
	s_waitcnt vmcnt(6)
	v_lshlrev_b32_e32 v72, 16, v220
	v_and_b32_e32 v36, 0xffff0000, v220
	v_or_b32_e32 v84, 11, v54
	v_add3_u32 v9, v9, v45, s27
	v_lshrrev_b32_e32 v45, 16, v73
	v_lshlrev_b32_e32 v73, 16, v221
	v_and_b32_e32 v37, 0xffff0000, v221
	v_ashrrev_i32_e32 v85, 31, v84
	v_pk_fma_f32 v[42:43], v[34:35], v[42:43], v[38:39]
	v_lshl_add_u64 v[84:85], s[2:3], 0, v[84:85]
	v_lshrrev_b32_e32 v8, 16, v8
	v_lshrrev_b32_e32 v9, 16, v9
	v_pk_fma_f32 v[42:43], v[18:19], v[60:61], v[42:43]
	v_lshlrev_b64 v[84:85], 11, v[84:85]
	v_and_or_b32 v91, v5, s26, v45
	v_and_or_b32 v89, v55, s26, v9
	v_and_or_b32 v88, v83, s26, v8
	v_pk_fma_f32 v[42:43], v[22:23], v[62:63], v[42:43]
	v_lshl_add_u64 v[84:85], v[52:53], 0, v[84:85]
	ds_write_b128 v4, v[88:91] offset:4224
	v_pk_fma_f32 v[8:9], v[46:47], v[70:71], v[50:51]
	v_pk_fma_f32 v[88:89], v[30:31], v[36:37], v[42:43]
	v_lshlrev_b32_e32 v71, 16, v223
	v_lshlrev_b32_e32 v70, 16, v222
	v_and_b32_e32 v43, 0xffff0000, v223
	v_and_b32_e32 v42, 0xffff0000, v222
	v_pk_fma_f32 v[58:59], v[14:15], v[58:59], v[26:27]
	v_pk_fma_f32 v[8:9], v[48:49], v[66:67], v[8:9]
	v_pk_fma_f32 v[58:59], v[2:3], v[24:25], v[58:59]
	v_pk_fma_f32 v[68:69], v[16:17], v[68:69], v[12:13]
	v_pk_fma_f32 v[58:59], v[6:7], v[28:29], v[58:59]
	v_pk_fma_f32 v[8:9], v[40:41], v[76:77], v[8:9]
	v_pk_fma_f32 v[68:69], v[32:33], v[64:65], v[68:69]
	v_pk_fma_f32 v[58:59], v[10:11], v[42:43], v[58:59]
	v_pk_fma_f32 v[8:9], v[56:57], v[72:73], v[8:9]
	v_pk_fma_f32 v[68:69], v[0:1], v[74:75], v[68:69]
	v_bfe_u32 v5, v59, 16, 1
	v_bfe_u32 v45, v58, 16, 1
	v_pk_fma_f32 v[68:69], v[20:21], v[70:71], v[68:69]
	v_bfe_u32 v83, v88, 16, 1
	v_add3_u32 v45, v58, v45, s27
	v_add3_u32 v5, v59, v5, s27
	v_bfe_u32 v58, v8, 16, 1
	v_bfe_u32 v59, v9, 16, 1
	v_bfe_u32 v55, v89, 16, 1
	v_add3_u32 v83, v88, v83, s27
	v_bfe_u32 v88, v68, 16, 1
	v_add3_u32 v9, v9, v59, s27
	v_add3_u32 v8, v8, v58, s27
	v_add3_u32 v55, v89, v55, s27
	v_bfe_u32 v89, v69, 16, 1
	v_add3_u32 v68, v68, v88, s27
	v_lshrrev_b32_e32 v8, 16, v8
	v_lshrrev_b32_e32 v9, 16, v9
	v_add3_u32 v69, v69, v89, s27
	v_lshrrev_b32_e32 v58, 16, v68
	v_and_or_b32 v89, v55, s26, v9
	v_and_or_b32 v88, v83, s26, v8
	v_pk_fma_f32 v[8:9], v[46:47], v[66:67], v[50:51]
	v_lshrrev_b32_e32 v59, 16, v69
	v_and_or_b32 v90, v45, s26, v58
	s_waitcnt vmcnt(5)
	v_lshlrev_b32_e32 v68, 16, v224
	v_and_b32_e32 v58, 0xffff0000, v224
	v_pk_fma_f32 v[8:9], v[48:49], v[76:77], v[8:9]
	v_or_b32_e32 v78, 12, v54
	v_and_or_b32 v91, v5, s26, v59
	v_lshlrev_b32_e32 v69, 16, v225
	v_and_b32_e32 v59, 0xffff0000, v225
	v_pk_fma_f32 v[8:9], v[40:41], v[72:73], v[8:9]
	v_ashrrev_i32_e32 v79, 31, v78
	ds_write_b128 v4, v[88:91] offset:4752
	v_pk_fma_f32 v[88:89], v[56:57], v[68:69], v[8:9]
	v_pk_fma_f32 v[8:9], v[34:35], v[60:61], v[38:39]
	v_lshl_add_u64 v[78:79], s[2:3], 0, v[78:79]
	v_pk_fma_f32 v[8:9], v[18:19], v[62:63], v[8:9]
	v_pk_fma_f32 v[24:25], v[14:15], v[24:25], v[26:27]
	v_lshlrev_b64 v[78:79], 11, v[78:79]
	v_pk_fma_f32 v[8:9], v[22:23], v[36:37], v[8:9]
	v_pk_fma_f32 v[64:65], v[16:17], v[64:65], v[12:13]
	v_pk_fma_f32 v[24:25], v[2:3], v[28:29], v[24:25]
	v_lshl_add_u64 v[78:79], v[52:53], 0, v[78:79]
	v_pk_fma_f32 v[60:61], v[30:31], v[58:59], v[8:9]
	v_lshlrev_b32_e32 v67, 16, v227
	v_lshlrev_b32_e32 v66, 16, v226
	v_and_b32_e32 v9, 0xffff0000, v227
	v_and_b32_e32 v8, 0xffff0000, v226
	v_pk_fma_f32 v[64:65], v[32:33], v[74:75], v[64:65]
	v_pk_fma_f32 v[24:25], v[6:7], v[42:43], v[24:25]
	v_pk_fma_f32 v[64:65], v[0:1], v[70:71], v[64:65]
	v_pk_fma_f32 v[24:25], v[10:11], v[8:9], v[24:25]
	v_pk_fma_f32 v[64:65], v[20:21], v[66:67], v[64:65]
	v_bfe_u32 v5, v25, 16, 1
	v_bfe_u32 v55, v61, 16, 1
	v_bfe_u32 v83, v60, 16, 1
	v_add3_u32 v55, v61, v55, s27
	v_add3_u32 v5, v25, v5, s27
	v_bfe_u32 v25, v88, 16, 1
	v_bfe_u32 v61, v64, 16, 1
	v_bfe_u32 v45, v24, 16, 1
	v_add3_u32 v60, v60, v83, s27
	v_bfe_u32 v83, v65, 16, 1
	v_add3_u32 v61, v64, v61, s27
	v_add3_u32 v25, v88, v25, s27
	v_add3_u32 v24, v24, v45, s27
	v_add3_u32 v65, v65, v83, s27
	v_lshrrev_b32_e32 v25, 16, v25
	v_lshrrev_b32_e32 v61, 16, v61
	v_lshrrev_b32_e32 v64, 16, v65
	v_and_or_b32 v90, v24, s26, v61
	v_and_or_b32 v88, v60, s26, v25
	v_pk_fma_f32 v[60:61], v[46:47], v[76:77], v[50:51]
	v_and_or_b32 v91, v5, s26, v64
	s_waitcnt vmcnt(4)
	v_lshlrev_b32_e32 v64, 16, v228
	v_and_b32_e32 v24, 0xffff0000, v228
	v_pk_fma_f32 v[60:61], v[48:49], v[72:73], v[60:61]
	v_or_b32_e32 v84, 13, v54
	v_bfe_u32 v45, v89, 16, 1
	v_lshlrev_b32_e32 v65, 16, v229
	v_and_b32_e32 v25, 0xffff0000, v229
	v_pk_fma_f32 v[60:61], v[40:41], v[68:69], v[60:61]
	v_ashrrev_i32_e32 v85, 31, v84
	v_add3_u32 v45, v89, v45, s27
	v_pk_fma_f32 v[76:77], v[56:57], v[64:65], v[60:61]
	v_pk_fma_f32 v[60:61], v[34:35], v[62:63], v[38:39]
	v_lshl_add_u64 v[84:85], s[2:3], 0, v[84:85]
	v_lshrrev_b32_e32 v45, 16, v45
	v_pk_fma_f32 v[60:61], v[18:19], v[36:37], v[60:61]
	v_lshlrev_b64 v[84:85], 11, v[84:85]
	v_and_or_b32 v89, v55, s26, v45
	v_pk_fma_f32 v[60:61], v[22:23], v[58:59], v[60:61]
	v_lshl_add_u64 v[84:85], v[52:53], 0, v[84:85]
	ds_write_b128 v4, v[88:91] offset:5280
	v_pk_fma_f32 v[88:89], v[30:31], v[24:25], v[60:61]
	v_lshlrev_b32_e32 v63, 16, v231
	v_lshlrev_b32_e32 v62, 16, v230
	v_and_b32_e32 v61, 0xffff0000, v231
	v_and_b32_e32 v60, 0xffff0000, v230
	v_pk_fma_f32 v[28:29], v[14:15], v[28:29], v[26:27]
	v_pk_fma_f32 v[74:75], v[16:17], v[74:75], v[12:13]
	v_pk_fma_f32 v[28:29], v[2:3], v[42:43], v[28:29]
	v_pk_fma_f32 v[74:75], v[32:33], v[70:71], v[74:75]
	v_pk_fma_f32 v[28:29], v[6:7], v[8:9], v[28:29]
	v_pk_fma_f32 v[74:75], v[0:1], v[66:67], v[74:75]
	v_pk_fma_f32 v[28:29], v[10:11], v[60:61], v[28:29]
	v_pk_fma_f32 v[74:75], v[20:21], v[62:63], v[74:75]
	v_bfe_u32 v5, v29, 16, 1
	v_bfe_u32 v83, v88, 16, 1
	v_bfe_u32 v45, v28, 16, 1
	v_bfe_u32 v55, v89, 16, 1
	v_add3_u32 v83, v88, v83, s27
	v_add3_u32 v5, v29, v5, s27
	v_bfe_u32 v29, v76, 16, 1
	v_bfe_u32 v88, v74, 16, 1
	v_add3_u32 v55, v89, v55, s27
	v_add3_u32 v28, v28, v45, s27
	v_bfe_u32 v45, v77, 16, 1
	v_bfe_u32 v89, v75, 16, 1
	v_add3_u32 v74, v74, v88, s27
	v_add3_u32 v29, v76, v29, s27
	v_add3_u32 v75, v75, v89, s27
	v_add3_u32 v45, v77, v45, s27
	v_lshrrev_b32_e32 v29, 16, v29
	v_lshrrev_b32_e32 v74, 16, v74
	v_lshrrev_b32_e32 v45, 16, v45
	v_lshrrev_b32_e32 v75, 16, v75
	v_and_or_b32 v76, v28, s26, v74
	v_and_or_b32 v74, v83, s26, v29
	v_pk_fma_f32 v[28:29], v[46:47], v[72:73], v[50:51]
	v_and_or_b32 v77, v5, s26, v75
	v_and_or_b32 v75, v55, s26, v45
	v_pk_fma_f32 v[28:29], v[48:49], v[68:69], v[28:29]
	ds_write_b128 v4, v[74:77] offset:5808
	s_waitcnt vmcnt(3)
	v_lshlrev_b32_e32 v77, 16, v233
	v_lshlrev_b32_e32 v76, 16, v232
	v_pk_fma_f32 v[28:29], v[40:41], v[64:65], v[28:29]
	v_and_b32_e32 v75, 0xffff0000, v233
	v_and_b32_e32 v74, 0xffff0000, v232
	v_pk_fma_f32 v[78:79], v[56:57], v[76:77], v[28:29]
	v_pk_fma_f32 v[28:29], v[34:35], v[36:37], v[38:39]
	v_or_b32_e32 v54, 14, v54
	v_pk_fma_f32 v[28:29], v[18:19], v[58:59], v[28:29]
	v_pk_fma_f32 v[42:43], v[14:15], v[42:43], v[26:27]
	v_ashrrev_i32_e32 v55, 31, v54
	v_pk_fma_f32 v[28:29], v[22:23], v[24:25], v[28:29]
	v_pk_fma_f32 v[70:71], v[16:17], v[70:71], v[12:13]
	v_pk_fma_f32 v[42:43], v[2:3], v[8:9], v[42:43]
	v_lshl_add_u64 v[54:55], s[2:3], 0, v[54:55]
	v_pk_fma_f32 v[88:89], v[30:31], v[74:75], v[28:29]
	v_and_b32_e32 v29, 0xffff0000, v235
	v_and_b32_e32 v28, 0xffff0000, v234
	v_pk_fma_f32 v[70:71], v[32:33], v[66:67], v[70:71]
	v_pk_fma_f32 v[42:43], v[6:7], v[60:61], v[42:43]
	v_lshlrev_b64 v[54:55], 11, v[54:55]
	v_lshlrev_b32_e32 v37, 16, v235
	v_lshlrev_b32_e32 v36, 16, v234
	v_pk_fma_f32 v[70:71], v[0:1], v[62:63], v[70:71]
	v_pk_fma_f32 v[42:43], v[10:11], v[28:29], v[42:43]
	v_lshl_add_u64 v[54:55], v[52:53], 0, v[54:55]
	v_pk_fma_f32 v[80:81], v[20:21], v[36:37], v[70:71]
	v_bfe_u32 v5, v43, 16, 1
	v_bfe_u32 v45, v42, 16, 1
	v_bfe_u32 v55, v88, 16, 1
	v_add3_u32 v55, v88, v55, s27
	v_add3_u32 v42, v42, v45, s27
	v_add3_u32 v5, v43, v5, s27
	v_bfe_u32 v43, v78, 16, 1
	v_bfe_u32 v45, v79, 16, 1
	v_bfe_u32 v83, v80, 16, 1
	v_bfe_u32 v88, v81, 16, 1
	v_bfe_u32 v54, v89, 16, 1
	v_add3_u32 v81, v81, v88, s27
	v_add3_u32 v80, v80, v83, s27
	v_add3_u32 v45, v79, v45, s27
	v_add3_u32 v43, v78, v43, s27
	v_add3_u32 v54, v89, v54, s27
	v_lshrrev_b32_e32 v43, 16, v43
	v_lshrrev_b32_e32 v45, 16, v45
	v_lshrrev_b32_e32 v78, 16, v80
	v_lshrrev_b32_e32 v79, 16, v81
	v_and_or_b32 v81, v5, s26, v79
	v_and_or_b32 v80, v42, s26, v78
	v_and_or_b32 v79, v54, s26, v45
	v_and_or_b32 v78, v55, s26, v43
	v_pk_fma_f32 v[54:55], v[46:47], v[68:69], v[50:51]
	s_waitcnt vmcnt(2)
	v_lshlrev_b32_e32 v43, 16, v237
	v_pk_fma_f32 v[54:55], v[48:49], v[64:65], v[54:55]
	v_lshlrev_b32_e32 v42, 16, v236
	v_pk_fma_f32 v[54:55], v[40:41], v[76:77], v[54:55]
	ds_write_b128 v4, v[78:81] offset:6336
	v_pk_fma_f32 v[68:69], v[56:57], v[42:43], v[54:55]
	v_pk_fma_f32 v[54:55], v[34:35], v[58:59], v[38:39]
	v_and_b32_e32 v79, 0xffff0000, v237
	v_pk_fma_f32 v[54:55], v[18:19], v[24:25], v[54:55]
	v_and_b32_e32 v78, 0xffff0000, v236
	v_pk_fma_f32 v[54:55], v[22:23], v[74:75], v[54:55]
	v_ashrrev_i32_e32 v83, 31, v82
	v_pk_fma_f32 v[58:59], v[30:31], v[78:79], v[54:55]
	v_pk_fma_f32 v[54:55], v[16:17], v[66:67], v[12:13]
	v_pk_fma_f32 v[8:9], v[14:15], v[8:9], v[26:27]
	v_pk_fma_f32 v[54:55], v[32:33], v[62:63], v[54:55]
	v_pk_fma_f32 v[8:9], v[2:3], v[60:61], v[8:9]
	v_pk_fma_f32 v[66:67], v[0:1], v[36:37], v[54:55]
	v_lshl_add_u64 v[54:55], s[2:3], 0, v[82:83]
	v_lshlrev_b64 v[54:55], 11, v[54:55]
	v_lshl_add_u64 v[52:53], v[52:53], 0, v[54:55]
	v_and_b32_e32 v85, 0xffff0000, v239
	v_and_b32_e32 v84, 0xffff0000, v238
	v_pk_fma_f32 v[8:9], v[6:7], v[28:29], v[8:9]
	v_lshlrev_b32_e32 v81, 16, v239
	v_lshlrev_b32_e32 v80, 16, v238
	v_pk_fma_f32 v[8:9], v[10:11], v[84:85], v[8:9]
	v_pk_fma_f32 v[66:67], v[20:21], v[80:81], v[66:67]
	v_bfe_u32 v5, v9, 16, 1
	v_bfe_u32 v45, v8, 16, 1
	v_bfe_u32 v83, v59, 16, 1
	v_bfe_u32 v86, v58, 16, 1
	v_add3_u32 v58, v58, v86, s27
	v_add3_u32 v59, v59, v83, s27
	v_add3_u32 v8, v8, v45, s27
	v_add3_u32 v5, v9, v5, s27
	v_bfe_u32 v9, v68, 16, 1
	v_bfe_u32 v45, v69, 16, 1
	v_bfe_u32 v83, v66, 16, 1
	v_bfe_u32 v86, v67, 16, 1
	v_add3_u32 v67, v67, v86, s27
	v_add3_u32 v66, v66, v83, s27
	v_add3_u32 v45, v69, v45, s27
	v_add3_u32 v9, v68, v9, s27
	v_lshrrev_b32_e32 v9, 16, v9
	v_lshrrev_b32_e32 v45, 16, v45
	v_lshrrev_b32_e32 v66, 16, v66
	v_lshrrev_b32_e32 v67, 16, v67
	v_pk_fma_f32 v[24:25], v[34:35], v[24:25], v[38:39]
	v_pk_fma_f32 v[60:61], v[14:15], v[60:61], v[26:27]
	v_and_or_b32 v69, v5, s26, v67
	v_and_or_b32 v68, v8, s26, v66
	v_and_or_b32 v67, v59, s26, v45
	v_and_or_b32 v66, v58, s26, v9
	v_pk_fma_f32 v[58:59], v[46:47], v[64:65], v[50:51]
	v_pk_fma_f32 v[24:25], v[18:19], v[74:75], v[24:25]
	v_pk_fma_f32 v[62:63], v[16:17], v[62:63], v[12:13]
	v_pk_fma_f32 v[60:61], v[2:3], v[28:29], v[60:61]
	ds_write_b128 v4, v[66:69] offset:6864
	s_waitcnt vmcnt(1)
	v_and_b32_e32 v67, 0xffff0000, v241
	v_and_b32_e32 v66, 0xffff0000, v240
	v_pk_fma_f32 v[58:59], v[48:49], v[76:77], v[58:59]
	v_pk_fma_f32 v[24:25], v[22:23], v[78:79], v[24:25]
	v_and_b32_e32 v69, 0xffff0000, v243
	v_and_b32_e32 v68, 0xffff0000, v242
	v_pk_fma_f32 v[62:63], v[32:33], v[36:37], v[62:63]
	v_pk_fma_f32 v[60:61], v[6:7], v[84:85], v[60:61]
	v_lshlrev_b32_e32 v9, 16, v241
	v_lshlrev_b32_e32 v8, 16, v240
	v_pk_fma_f32 v[58:59], v[40:41], v[42:43], v[58:59]
	v_pk_fma_f32 v[24:25], v[30:31], v[66:67], v[24:25]
	v_lshlrev_b32_e32 v65, 16, v243
	v_lshlrev_b32_e32 v64, 16, v242
	v_pk_fma_f32 v[62:63], v[0:1], v[80:81], v[62:63]
	v_pk_fma_f32 v[60:61], v[10:11], v[68:69], v[60:61]
	v_pk_fma_f32 v[58:59], v[56:57], v[8:9], v[58:59]
	v_pk_fma_f32 v[62:63], v[20:21], v[64:65], v[62:63]
	v_bfe_u32 v5, v61, 16, 1
	v_bfe_u32 v45, v60, 16, 1
	v_bfe_u32 v70, v25, 16, 1
	v_bfe_u32 v71, v24, 16, 1
	v_add3_u32 v24, v24, v71, s27
	v_add3_u32 v25, v25, v70, s27
	v_add3_u32 v45, v60, v45, s27
	v_add3_u32 v5, v61, v5, s27
	v_bfe_u32 v60, v58, 16, 1
	v_bfe_u32 v61, v59, 16, 1
	v_bfe_u32 v70, v62, 16, 1
	v_bfe_u32 v71, v63, 16, 1
	v_add3_u32 v63, v63, v71, s27
	v_add3_u32 v62, v62, v70, s27
	v_add3_u32 v59, v59, v61, s27
	v_add3_u32 v58, v58, v60, s27
	v_lshrrev_b32_e32 v58, 16, v58
	v_lshrrev_b32_e32 v59, 16, v59
	v_lshrrev_b32_e32 v60, 16, v62
	v_lshrrev_b32_e32 v61, 16, v63
	v_pk_fma_f32 v[46:47], v[46:47], v[76:77], v[50:51]
	v_and_or_b32 v61, v5, s26, v61
	v_and_or_b32 v60, v45, s26, v60
	v_and_or_b32 v59, v25, s26, v59
	v_and_or_b32 v58, v24, s26, v58
	v_pk_fma_f32 v[42:43], v[48:49], v[42:43], v[46:47]
	v_pk_fma_f32 v[12:13], v[16:17], v[36:37], v[12:13]
	ds_write_b128 v4, v[92:95]
	ds_write_b128 v4, v[58:61] offset:7392
	s_waitcnt vmcnt(0)
	v_lshlrev_b32_e32 v5, 16, v249
	v_lshlrev_b32_e32 v4, 16, v248
	v_pk_fma_f32 v[8:9], v[40:41], v[8:9], v[42:43]
	v_pk_fma_f32 v[12:13], v[32:33], v[80:81], v[12:13]
	v_pk_fma_f32 v[4:5], v[56:57], v[4:5], v[8:9]
	v_pk_fma_f32 v[8:9], v[34:35], v[74:75], v[38:39]
	v_pk_fma_f32 v[0:1], v[0:1], v[64:65], v[12:13]
	v_pk_fma_f32 v[12:13], v[14:15], v[28:29], v[26:27]
	v_pk_fma_f32 v[8:9], v[18:19], v[78:79], v[8:9]
	v_pk_fma_f32 v[2:3], v[2:3], v[84:85], v[12:13]
	v_and_b32_e32 v25, 0xffff0000, v249
	v_and_b32_e32 v24, 0xffff0000, v248
	v_pk_fma_f32 v[8:9], v[22:23], v[66:67], v[8:9]
	v_and_b32_e32 v23, 0xffff0000, v251
	v_and_b32_e32 v22, 0xffff0000, v250
	v_pk_fma_f32 v[2:3], v[6:7], v[68:69], v[2:3]
	v_pk_fma_f32 v[8:9], v[30:31], v[24:25], v[8:9]
	v_lshlrev_b32_e32 v19, 16, v251
	v_lshlrev_b32_e32 v18, 16, v250
	v_pk_fma_f32 v[2:3], v[10:11], v[22:23], v[2:3]
	v_pk_fma_f32 v[0:1], v[20:21], v[18:19], v[0:1]
	v_bfe_u32 v6, v3, 16, 1
	v_bfe_u32 v7, v2, 16, 1
	v_bfe_u32 v10, v9, 16, 1
	v_bfe_u32 v11, v8, 16, 1
	v_add3_u32 v8, v8, v11, s27
	v_add3_u32 v9, v9, v10, s27
	v_add3_u32 v2, v2, v7, s27
	v_add3_u32 v3, v3, v6, s27
	v_bfe_u32 v6, v4, 16, 1
	v_bfe_u32 v7, v5, 16, 1
	v_bfe_u32 v10, v0, 16, 1
	v_bfe_u32 v11, v1, 16, 1
	v_add3_u32 v1, v1, v11, s27
	v_add3_u32 v0, v0, v10, s27
	v_add3_u32 v5, v5, v7, s27
	v_add3_u32 v4, v4, v6, s27
	v_lshrrev_b32_e32 v4, 16, v4
	v_lshrrev_b32_e32 v5, 16, v5
	v_lshrrev_b32_e32 v0, 16, v0
	v_lshrrev_b32_e32 v1, 16, v1
	v_and_or_b32 v3, v3, s26, v1
	v_and_or_b32 v2, v2, s26, v0
	v_and_or_b32 v1, v9, s26, v5
	v_and_or_b32 v0, v8, s26, v4
	v_mad_u64_u32 v[4:5], s[0:1], v82, s30, v[44:45]
	s_lshl_b32 s62, s47, 5
	ds_write_b128 v4, v[0:3]
	v_and_b32_e32 v4, 31, v96
	s_add_i32 s0, s62, s6
	v_or_b32_e32 v0, s0, v4
	s_ashr_i32 s0, s0, 7
	s_ashr_i32 s1, s0, 31
	s_lshl_b64 s[0:1], s[0:1], 16
	v_lshlrev_b32_e32 v1, 8, v0
	s_add_u32 s0, s40, s0
	v_bfe_u32 v97, v96, 5, 1
	v_and_b32_e32 v108, 0x7f00, v1
	s_addc_u32 s1, s41, s1
	v_lshl_add_u64 v[2:3], s[0:1], 0, v[108:109]
	v_lshlrev_b32_e32 v108, 4, v97
	v_lshl_add_u64 v[2:3], v[2:3], 0, v[108:109]
	s_mov_b64 s[0:1], 0x8000
	s_waitcnt lgkmcnt(0)
	s_barrier
	v_lshl_add_u64 v[6:7], v[2:3], 0, s[0:1]
	global_load_dwordx4 v[32:35], v[2:3], off
	global_load_dwordx4 v[36:39], v[2:3], off offset:32
	global_load_dwordx4 v[40:43], v[6:7], off offset:32
	global_load_dwordx4 v[44:47], v[6:7], off offset:64
	global_load_dwordx4 v[48:51], v[2:3], off offset:64
	global_load_dwordx4 v[52:55], v[2:3], off offset:96
	global_load_dwordx4 v[56:59], v[6:7], off offset:96
	global_load_dwordx4 v[60:63], v[6:7], off offset:128
	global_load_dwordx4 v[64:67], v[2:3], off offset:128
	global_load_dwordx4 v[68:71], v[2:3], off offset:160
	global_load_dwordx4 v[72:75], v[6:7], off offset:160
	global_load_dwordx4 v[76:79], v[6:7], off offset:192
	global_load_dwordx4 v[80:83], v[2:3], off offset:192
	global_load_dwordx4 v[84:87], v[2:3], off offset:224
	s_mov_b32 s0, 0x8000
	v_add_co_u32_e32 v8, vcc, s0, v2
	v_ashrrev_i32_e32 v1, 31, v0
	s_nop 0
	v_addc_co_u32_e32 v9, vcc, 0, v3, vcc
	v_lshlrev_b64 v[2:3], 2, v[0:1]
	v_lshl_add_u64 v[10:11], s[70:71], 0, v[2:3]
	global_load_dword v10, v[10:11], off
	s_nop 0
	global_load_dwordx4 v[88:91], v[8:9], off
	global_load_dwordx4 v[92:95], v[6:7], off offset:224
	v_lshl_add_u64 v[6:7], s[64:65], 0, v[2:3]
	v_lshl_add_u64 v[2:3], s[68:69], 0, v[2:3]
	global_load_dword v6, v[6:7], off
	s_mov_b32 s0, 0x41700000
	global_load_dword v5, v[2:3], off
	s_waitcnt vmcnt(4)
	v_mul_f32_e32 v2, 0xbfb8aa3b, v10
	v_exp_f32_e32 v7, v2
	v_cmp_nlt_f32_e32 vcc, s0, v10
	s_and_saveexec_b64 s[0:1], vcc
	s_cbranch_execz .LBB0_457
	v_add_f32_e32 v8, 1.0, v7
	v_add_f32_e32 v2, -1.0, v8
	v_sub_f32_e32 v3, v2, v8
	v_add_f32_e32 v3, 1.0, v3
	v_sub_f32_e32 v2, v7, v2
	v_add_f32_e32 v9, v2, v3
	v_frexp_mant_f32_e32 v10, v8
	v_cvt_f64_f32_e32 v[2:3], v8
	s_mov_b32 s2, 0x3f2aaaab
	v_frexp_exp_i32_f64_e32 v2, v[2:3]
	v_cmp_gt_f32_e32 vcc, s2, v10
	s_mov_b32 s2, 0x3f317218
	s_nop 0
	v_subbrev_co_u32_e32 v14, vcc, 0, v2, vcc
	v_sub_u32_e32 v2, 0, v14
	v_ldexp_f32 v3, v8, v2
	v_add_f32_e32 v8, -1.0, v3
	v_add_f32_e32 v10, 1.0, v3
	v_ldexp_f32 v2, v9, v2
	v_add_f32_e32 v9, 1.0, v8
	v_add_f32_e32 v11, -1.0, v10
	v_sub_f32_e32 v9, v3, v9
	v_sub_f32_e32 v3, v3, v11
	v_add_f32_e32 v9, v2, v9
	v_add_f32_e32 v2, v2, v3
	v_add_f32_e32 v15, v10, v2
	v_rcp_f32_e32 v17, v15
	v_sub_f32_e32 v3, v15, v10
	v_sub_f32_e32 v16, v2, v3
	v_add_f32_e32 v3, v8, v9
	v_mul_f32_e32 v19, v3, v17
	v_sub_f32_e32 v2, v3, v8
	v_mul_f32_e32 v8, v15, v19
	v_fma_f32 v10, v19, v15, -v8
	v_fmac_f32_e32 v10, v19, v16
	v_sub_f32_e32 v18, v9, v2
	v_add_f32_e32 v2, v8, v10
	v_sub_f32_e32 v9, v3, v2
	v_pk_add_f32 v[12:13], v[2:3], v[8:9] neg_lo:[0,1] neg_hi:[0,1]
	v_mov_b32_e32 v11, v2
	v_pk_add_f32 v[2:3], v[12:13], v[10:11] neg_lo:[0,1] neg_hi:[0,1]
	s_nop 0
	v_add_f32_e32 v3, v18, v3
	v_add_f32_e32 v2, v2, v3
	v_add_f32_e32 v3, v9, v2
	v_mul_f32_e32 v18, v17, v3
	v_mul_f32_e32 v8, v15, v18
	v_fma_f32 v10, v18, v15, -v8
	v_fmac_f32_e32 v10, v18, v16
	v_sub_f32_e32 v9, v9, v3
	v_add_f32_e32 v15, v2, v9
	v_add_f32_e32 v2, v8, v10
	v_sub_f32_e32 v9, v3, v2
	v_pk_add_f32 v[12:13], v[2:3], v[8:9] neg_lo:[0,1] neg_hi:[0,1]
	v_mov_b32_e32 v11, v2
	v_pk_add_f32 v[2:3], v[12:13], v[10:11] neg_lo:[0,1] neg_hi:[0,1]
	s_nop 0
	v_add_f32_e32 v3, v15, v3
	v_add_f32_e32 v2, v2, v3
	v_add_f32_e32 v3, v19, v18
	v_add_f32_e32 v2, v9, v2
	v_sub_f32_e32 v8, v3, v19
	v_mul_f32_e32 v2, v17, v2
	v_sub_f32_e32 v8, v18, v8
	v_add_f32_e32 v8, v8, v2
	v_add_f32_e32 v10, v3, v8
	v_mul_f32_e32 v11, v10, v10
	v_fmamk_f32 v2, v11, 0x3e9b6dac, v134
	v_fmaak_f32 v111, v11, v2, 0x3f2aaada
	v_cvt_f32_i32_e32 v2, v14
	v_sub_f32_e32 v3, v10, v3
	v_sub_f32_e32 v3, v8, v3
	v_ldexp_f32 v12, v3, 1
	v_mul_f32_e32 v3, v10, v11
	v_ldexp_f32 v9, v10, 1
	v_pk_mul_f32 v[10:11], v[2:3], v[110:111]
	s_nop 0
	v_fma_f32 v8, v2, s2, -v10
	v_fmac_f32_e32 v8, 0xb102e308, v2
	v_pk_add_f32 v[2:3], v[10:11], v[8:9]
	s_mov_b32 s2, 0x7f800000
	v_sub_f32_e32 v9, v3, v9
	v_sub_f32_e32 v9, v11, v9
	v_add_f32_e32 v13, v12, v9
	v_mov_b32_e32 v12, v10
	v_pk_add_f32 v[10:11], v[2:3], v[10:11] neg_lo:[0,1] neg_hi:[0,1]
	v_pk_add_f32 v[14:15], v[2:3], v[12:13]
	v_mov_b32_e32 v9, v2
	v_mov_b32_e32 v11, v15
	v_pk_add_f32 v[16:17], v[8:9], v[10:11] neg_lo:[0,1] neg_hi:[0,1]
	v_pk_add_f32 v[8:9], v[8:9], v[10:11]
	v_mov_b32_e32 v12, v13
	v_pk_add_f32 v[10:11], v[8:9], v[2:3] op_sel:[1,0] op_sel_hi:[0,1] neg_lo:[0,1] neg_hi:[0,1]
	v_pk_add_f32 v[18:19], v[14:15], v[10:11] op_sel_hi:[1,0] neg_lo:[0,1] neg_hi:[0,1]
	v_mov_b32_e32 v14, v15
	v_mov_b32_e32 v15, v9
	v_pk_mov_b32 v[10:11], v[2:3], v[10:11] op_sel:[1,0]
	v_mov_b32_e32 v13, v2
	v_pk_add_f32 v[10:11], v[14:15], v[10:11] neg_lo:[0,1] neg_hi:[0,1]
	v_mov_b32_e32 v18, v16
	v_pk_add_f32 v[2:3], v[12:13], v[10:11] neg_lo:[0,1] neg_hi:[0,1]
	v_mov_b32_e32 v17, v9
	v_pk_add_f32 v[10:11], v[18:19], v[2:3]
	v_cmp_neq_f32_e32 vcc, s2, v7
	v_pk_add_f32 v[12:13], v[10:11], v[10:11] op_sel:[0,1] op_sel_hi:[1,0]
	s_mov_b32 s2, 0x33800000
	v_pk_add_f32 v[8:9], v[8:9], v[12:13] op_sel:[1,0] op_sel_hi:[0,1]
	v_mov_b32_e32 v11, v8
	v_pk_add_f32 v[14:15], v[10:11], v[16:17] neg_lo:[0,1] neg_hi:[0,1]
	v_mov_b32_e32 v3, v12
	v_sub_f32_e32 v9, v10, v14
	v_pk_add_f32 v[2:3], v[2:3], v[14:15] neg_lo:[0,1] neg_hi:[0,1]
	v_sub_f32_e32 v9, v16, v9
	v_add_f32_e32 v2, v2, v9
	v_add_f32_e32 v2, v2, v3
	v_add_f32_e32 v2, v8, v2
	v_cndmask_b32_e32 v2, v135, v2, vcc
	v_cmp_ngt_f32_e32 vcc, -1.0, v7
	s_nop 1
	v_cndmask_b32_e32 v2, v136, v2, vcc
	v_cmp_neq_f32_e32 vcc, -1.0, v7
	s_nop 1
	v_cndmask_b32_e32 v2, v137, v2, vcc
	v_cmp_lt_f32_e64 vcc, |v7|, s2
	s_nop 1
	v_cndmask_b32_e32 v7, v2, v7, vcc
